# P1 and P5 GEMM epilogues: the eight row-statistic loads issued together (were serialized behind vmcnt(0))
# speedup vs baseline: 1.0420x; 1.0091x over previous
.LBB0_248:
	v_and_b32_e32 v131, 64, v197
	v_xor_b32_e32 v130, 16, v197
	v_add_u32_e32 v131, 64, v131
	v_cmp_lt_i32_e32 vcc, v130, v131
	s_lshl_b32 s92, s31, 8
	v_add_u32_e32 v146, s35, v128
	v_cndmask_b32_e32 v130, v197, v130, vcc
	v_lshlrev_b32_e32 v147, 2, v130
	v_xor_b32_e32 v130, 32, v197
	v_add_u32_e32 v158, s92, v146
	v_lshlrev_b32_e32 v128, 2, v134
	v_cmp_lt_i32_e32 vcc, v130, v131
	v_ashrrev_i32_e32 v129, 31, v128
	v_ashrrev_i32_e32 v159, 31, v158
	v_cndmask_b32_e32 v130, v197, v130, vcc
	v_lshl_add_u64 v[128:129], v[128:129], 2, s[60:61]
	v_lshlrev_b32_e32 v135, 2, v130
	v_lshlrev_b64 v[130:131], 6, v[158:159]
	v_lshl_add_u64 v[130:131], v[128:129], 0, v[130:131]
	global_load_dwordx4 v[176:179], v[130:131], off offset:1024
	global_load_dwordx4 v[180:183], v[130:131], off offset:2048
	global_load_dwordx4 v[184:187], v[130:131], off offset:3072
	v_add_co_u32_e32 v226, vcc, 0x2000, v130
	s_nop 1
	v_addc_co_u32_e32 v227, vcc, 0, v131, vcc
	global_load_dwordx4 v[188:191], v[226:227], off
	global_load_dwordx4 v[198:201], v[226:227], off offset:1024
	global_load_dwordx4 v[218:221], v[226:227], off offset:2048
	global_load_dwordx4 v[222:225], v[226:227], off offset:3072
	global_load_dwordx4 v[130:133], v[130:131], off
	s_waitcnt vmcnt(0)
	v_mov_b32_e32 v148, v131
	v_mov_b32_e32 v149, v132
	v_mov_b32_e32 v131, v133
	v_pk_add_f32 v[148:149], v[148:149], v[130:131]
	v_add_u32_e32 v130, 16, v158
	v_ashrrev_i32_e32 v131, 31, v130
	v_lshlrev_b64 v[130:131], 6, v[130:131]
	v_lshl_add_u64 v[130:131], v[128:129], 0, v[130:131]
	v_mov_b32_e32 v130, v176
	v_mov_b32_e32 v131, v177
	v_mov_b32_e32 v132, v178
	v_mov_b32_e32 v133, v179
	v_mov_b32_e32 v150, v131
	v_mov_b32_e32 v151, v132
	v_mov_b32_e32 v131, v133
	v_pk_add_f32 v[130:131], v[150:151], v[130:131]
	v_mov_b32_e32 v133, v148
	v_mov_b32_e32 v132, v130
	v_mov_b32_e32 v148, v131
	v_pk_add_f32 v[130:131], v[132:133], v[148:149]
	ds_bpermute_b32 v133, v147, v131
	ds_bpermute_b32 v132, v147, v130
	s_waitcnt lgkmcnt(0)
	v_pk_add_f32 v[130:131], v[130:131], v[132:133]
	ds_bpermute_b32 v133, v135, v131
	ds_bpermute_b32 v132, v135, v130
	s_waitcnt lgkmcnt(0)
	v_pk_add_f32 v[130:131], v[130:131], v[132:133]
	s_nop 0
	v_pk_fma_f32 v[164:165], v[130:131], s[66:67], v[196:197] op_sel_hi:[1,0,0]
	s_nop 0
	v_mul_f32_e32 v130, 0x4b800000, v165
	v_cmp_gt_f32_e32 vcc, s80, v165
	v_cmp_gt_f32_e64 s[0:1], s80, v164
	s_nop 0
	v_cndmask_b32_e32 v130, v165, v130, vcc
	v_rsq_f32_e32 v130, v130
	s_nop 0
	v_mul_f32_e32 v131, 0x45800000, v130
	v_cndmask_b32_e32 v166, v130, v131, vcc
	v_add_u32_e32 v130, 32, v158
	v_ashrrev_i32_e32 v131, 31, v130
	v_lshlrev_b64 v[130:131], 6, v[130:131]
	v_lshl_add_u64 v[130:131], v[128:129], 0, v[130:131]
	v_mov_b32_e32 v130, v180
	v_mov_b32_e32 v131, v181
	v_mov_b32_e32 v132, v182
	v_mov_b32_e32 v133, v183
	s_add_i32 vcc_lo, s30, -6
	s_cmp_gt_u32 vcc_lo, 7
	s_cselect_b64 s[30:31], -1, 0
	s_ashr_i32 s7, s6, 31
	s_lshl_b64 s[6:7], s[6:7], 1
	s_add_u32 s48, s4, s6
	s_addc_u32 s49, s5, s7
	s_cmp_lg_u64 s[96:97], 0
	s_cselect_b64 s[28:29], -1, 0
	s_xor_b64 s[6:7], s[88:89], -1
	s_and_b64 s[88:89], s[6:7], s[28:29]
	s_mov_b64 s[4:5], -1
	s_cmp_lt_u32 vcc_lo, 8
	v_mov_b32_e32 v148, v131
	v_mov_b32_e32 v149, v132
	v_mov_b32_e32 v131, v133
	v_pk_add_f32 v[148:149], v[148:149], v[130:131]
	v_add_u32_e32 v130, 48, v158
	v_ashrrev_i32_e32 v131, 31, v130
	v_lshlrev_b64 v[130:131], 6, v[130:131]
	v_lshl_add_u64 v[130:131], v[128:129], 0, v[130:131]
	v_mov_b32_e32 v130, v184
	v_mov_b32_e32 v131, v185
	v_mov_b32_e32 v132, v186
	v_mov_b32_e32 v133, v187
	v_mov_b32_e32 v150, v131
	v_mov_b32_e32 v151, v132
	v_mov_b32_e32 v131, v133
	v_pk_add_f32 v[130:131], v[150:151], v[130:131]
	v_mov_b32_e32 v133, v148
	v_mov_b32_e32 v132, v130
	v_mov_b32_e32 v148, v131
	v_pk_add_f32 v[130:131], v[132:133], v[148:149]
	ds_bpermute_b32 v133, v147, v131
	ds_bpermute_b32 v132, v147, v130
	s_waitcnt lgkmcnt(0)
	v_pk_add_f32 v[160:161], v[130:131], v[132:133]
	v_add_u32_e32 v130, 0x80, v158
	v_ashrrev_i32_e32 v131, 31, v130
	v_lshlrev_b64 v[130:131], 6, v[130:131]
	v_lshl_add_u64 v[130:131], v[128:129], 0, v[130:131]
	v_mov_b32_e32 v130, v188
	v_mov_b32_e32 v131, v189
	v_mov_b32_e32 v132, v190
	v_mov_b32_e32 v133, v191
	ds_bpermute_b32 v163, v135, v161
	ds_bpermute_b32 v162, v135, v160
	v_mov_b32_e32 v148, v131
	v_mov_b32_e32 v149, v132
	v_mov_b32_e32 v131, v133
	v_pk_add_f32 v[148:149], v[148:149], v[130:131]
	v_add_u32_e32 v130, 0x90, v158
	v_ashrrev_i32_e32 v131, 31, v130
	v_lshlrev_b64 v[130:131], 6, v[130:131]
	v_lshl_add_u64 v[130:131], v[128:129], 0, v[130:131]
	v_mov_b32_e32 v130, v198
	v_mov_b32_e32 v131, v199
	v_mov_b32_e32 v132, v200
	v_mov_b32_e32 v133, v201
	v_mov_b32_e32 v150, v131
	v_mov_b32_e32 v151, v132
	v_mov_b32_e32 v131, v133
	v_pk_add_f32 v[130:131], v[150:151], v[130:131]
	v_mov_b32_e32 v133, v148
	v_mov_b32_e32 v132, v130
	v_mov_b32_e32 v148, v131
	v_pk_add_f32 v[130:131], v[132:133], v[148:149]
	ds_bpermute_b32 v133, v147, v131
	ds_bpermute_b32 v132, v147, v130
	s_waitcnt lgkmcnt(0)
	v_pk_add_f32 v[150:151], v[130:131], v[132:133]
	v_add_u32_e32 v130, 0xa0, v158
	v_ashrrev_i32_e32 v131, 31, v130
	v_lshlrev_b64 v[130:131], 6, v[130:131]
	v_lshl_add_u64 v[130:131], v[128:129], 0, v[130:131]
	v_mov_b32_e32 v130, v218
	v_mov_b32_e32 v131, v219
	v_mov_b32_e32 v132, v220
	v_mov_b32_e32 v133, v221
	ds_bpermute_b32 v153, v135, v151
	ds_bpermute_b32 v152, v135, v150
	v_mov_b32_e32 v148, v131
	v_mov_b32_e32 v149, v132
	v_mov_b32_e32 v131, v133
	v_pk_add_f32 v[132:133], v[148:149], v[130:131]
	v_add_u32_e32 v130, 0xb0, v158
	v_ashrrev_i32_e32 v131, 31, v130
	v_lshlrev_b64 v[130:131], 6, v[130:131]
	v_lshl_add_u64 v[128:129], v[128:129], 0, v[130:131]
	v_mov_b32_e32 v128, v222
	v_mov_b32_e32 v129, v223
	v_mov_b32_e32 v130, v224
	v_mov_b32_e32 v131, v225
	v_mov_b32_e32 v148, v129
	v_mov_b32_e32 v149, v130
	v_mov_b32_e32 v129, v131
	v_pk_add_f32 v[128:129], v[148:149], v[128:129]
	v_mov_b32_e32 v131, v132
	v_mov_b32_e32 v130, v128
	v_mov_b32_e32 v132, v129
	v_pk_add_f32 v[128:129], v[130:131], v[132:133]
	ds_bpermute_b32 v131, v147, v129
	ds_bpermute_b32 v130, v147, v128
	v_lshl_add_u32 v148, v134, 3, s26
	v_ashrrev_i32_e32 v149, 31, v148
	s_waitcnt lgkmcnt(0)
	v_pk_add_f32 v[154:155], v[128:129], v[130:131]
	ds_bpermute_b32 v157, v135, v155
	ds_bpermute_b32 v156, v135, v154
	s_cbranch_scc1 .LBB0_254
	v_mul_lo_u32 v130, s25, v158
	v_mul_lo_u32 v131, s24, v159
	v_mad_u64_u32 v[128:129], s[4:5], s24, v158, 0
	v_add3_u32 v129, v129, v131, v130
	v_ashrrev_i32_e32 v147, 31, v146
	v_lshl_add_u64 v[168:169], v[128:129], 1, s[48:49]
	v_lshlrev_b64 v[128:129], 10, v[146:147]
	v_lshl_add_u64 v[180:181], s[96:97], 0, v[128:129]
	v_pk_mul_f32 v[130:131], v[122:123], v[166:167] op_sel_hi:[1,0]
	v_pk_mul_f32 v[128:129], v[120:121], v[166:167] op_sel_hi:[1,0]
	v_pk_mul_f32 v[134:135], v[118:119], v[166:167] op_sel_hi:[1,0]
	v_pk_mul_f32 v[132:133], v[116:117], v[166:167] op_sel_hi:[1,0]
	v_cvt_pk_bf16_f32 v176, v128, v129
	v_cvt_pk_bf16_f32 v177, v130, v131
	v_cvt_pk_bf16_f32 v178, v132, v133
	v_cvt_pk_bf16_f32 v179, v134, v135
	v_lshl_add_u64 v[170:171], v[148:149], 1, v[168:169]
	s_and_b64 vcc, exec, s[88:89]
	v_lshl_add_u64 v[168:169], v[148:149], 2, v[180:181]
	global_store_dwordx4 v[170:171], v[176:179], off
	s_cbranch_vccz .LBB0_251
	global_store_dwordx4 v[168:169], v[128:131], off
	global_store_dwordx4 v[168:169], v[132:135], off offset:16

.LBB0_786:
	v_and_b32_e32 v131, 64, v197
	v_xor_b32_e32 v130, 16, v197
	v_add_u32_e32 v131, 64, v131
	v_cmp_lt_i32_e32 vcc, v130, v131
	v_mov_b32_e32 v128, v149
	v_mov_b32_e32 v165, v147
	s_lshl_b32 s4, s55, 8
	v_cndmask_b32_e32 v130, v197, v130, vcc
	s_add_i32 s4, s4, s33
	v_lshlrev_b32_e32 v174, 2, v130
	v_xor_b32_e32 v130, 32, v197
	v_add_u32_e32 v142, s4, v128
	v_lshlrev_b32_e32 v128, 2, v165
	v_cmp_lt_i32_e32 vcc, v130, v131
	v_ashrrev_i32_e32 v129, 31, v128
	v_ashrrev_i32_e32 v143, 31, v142
	v_cndmask_b32_e32 v130, v197, v130, vcc
	v_lshl_add_u64 v[128:129], v[128:129], 2, s[12:13]
	v_lshlrev_b32_e32 v167, 2, v130
	v_lshlrev_b64 v[130:131], 6, v[142:143]
	v_lshl_add_u64 v[130:131], v[128:129], 0, v[130:131]
	global_load_dwordx4 v[178:181], v[130:131], off offset:1024
	global_load_dwordx4 v[182:185], v[130:131], off offset:2048
	global_load_dwordx4 v[186:189], v[130:131], off offset:3072
	v_add_co_u32_e32 v230, vcc, 0x2000, v130
	s_nop 1
	v_addc_co_u32_e32 v231, vcc, 0, v131, vcc
	global_load_dwordx4 v[198:201], v[230:231], off
	global_load_dwordx4 v[218:221], v[230:231], off offset:1024
	global_load_dwordx4 v[222:225], v[230:231], off offset:2048
	global_load_dwordx4 v[226:229], v[230:231], off offset:3072
	global_load_dwordx4 v[150:153], v[130:131], off
	v_add_u32_e32 v144, 16, v142
	v_ashrrev_i32_e32 v145, 31, v144
	s_mov_b32 s4, 0x358637bd
	s_waitcnt vmcnt(0)
	v_mov_b32_e32 v130, v151
	v_mov_b32_e32 v131, v152
	v_mov_b32_e32 v151, v153
	v_pk_add_f32 v[130:131], v[130:131], v[150:151]
	v_lshlrev_b64 v[150:151], 6, v[144:145]
	v_lshl_add_u64 v[150:151], v[128:129], 0, v[150:151]
	v_mov_b32_e32 v150, v178
	v_mov_b32_e32 v151, v179
	v_mov_b32_e32 v152, v180
	v_mov_b32_e32 v153, v181
	v_mov_b32_e32 v156, v151
	v_mov_b32_e32 v157, v152
	v_mov_b32_e32 v151, v153
	v_pk_add_f32 v[150:151], v[156:157], v[150:151]
	v_mov_b32_e32 v153, v130
	v_mov_b32_e32 v152, v150
	v_mov_b32_e32 v130, v151
	v_pk_add_f32 v[130:131], v[152:153], v[130:131]
	ds_bpermute_b32 v151, v174, v131
	ds_bpermute_b32 v150, v174, v130
	v_mov_b64_e32 v[156:157], s[4:5]
	v_add_u32_e32 v152, 32, v142
	v_ashrrev_i32_e32 v153, 31, v152
	s_waitcnt lgkmcnt(0)
	v_pk_add_f32 v[130:131], v[130:131], v[150:151]
	ds_bpermute_b32 v151, v167, v131
	ds_bpermute_b32 v150, v167, v130
	s_waitcnt lgkmcnt(0)
	v_pk_add_f32 v[130:131], v[130:131], v[150:151]
	s_nop 0
	v_pk_fma_f32 v[130:131], v[130:131], s[66:67], v[156:157] op_sel_hi:[1,0,0]
	v_add_u32_e32 v150, 48, v142
	v_mul_f32_e32 v146, 0x4b800000, v131
	v_cmp_gt_f32_e64 s[4:5], s80, v131
	v_cmp_gt_f32_e32 vcc, s80, v130
	v_ashrrev_i32_e32 v151, 31, v150
	v_cndmask_b32_e64 v131, v131, v146, s[4:5]
	v_rsq_f32_e32 v131, v131
	s_nop 0
	v_mul_f32_e32 v146, 0x45800000, v131
	v_cndmask_b32_e64 v148, v131, v146, s[4:5]
	v_mul_f32_e32 v131, 0x4b800000, v130
	v_cndmask_b32_e32 v130, v130, v131, vcc
	v_rsq_f32_e32 v130, v130
	v_pk_mul_f32 v[124:125], v[124:125], v[148:149] op_sel_hi:[1,0]
	v_pk_mul_f32 v[120:121], v[120:121], v[148:149] op_sel_hi:[1,0]
	v_pk_mul_f32 v[126:127], v[126:127], v[148:149] op_sel_hi:[1,0]
	v_mul_f32_e32 v131, 0x45800000, v130
	v_cndmask_b32_e32 v146, v130, v131, vcc
	v_lshlrev_b64 v[130:131], 6, v[152:153]
	v_lshl_add_u64 v[130:131], v[128:129], 0, v[130:131]
	v_mov_b32_e32 v160, v182
	v_mov_b32_e32 v161, v183
	v_mov_b32_e32 v162, v184
	v_mov_b32_e32 v163, v185
	v_pk_mul_f32 v[118:119], v[118:119], v[148:149] op_sel_hi:[1,0]
	v_pk_mul_f32 v[116:117], v[116:117], v[148:149] op_sel_hi:[1,0]
	v_pk_mul_f32 v[108:109], v[108:109], v[146:147] op_sel_hi:[1,0]
	v_pk_mul_f32 v[110:111], v[110:111], v[146:147] op_sel_hi:[1,0]
	v_pk_mul_f32 v[102:103], v[102:103], v[146:147] op_sel_hi:[1,0]
	v_pk_mul_f32 v[100:101], v[100:101], v[146:147] op_sel_hi:[1,0]
	v_mov_b32_e32 v130, v161
	v_mov_b32_e32 v131, v162
	v_mov_b32_e32 v161, v163
	v_pk_add_f32 v[130:131], v[130:131], v[160:161]
	v_lshlrev_b64 v[160:161], 6, v[150:151]
	v_lshl_add_u64 v[160:161], v[128:129], 0, v[160:161]
	v_mov_b32_e32 v160, v186
	v_mov_b32_e32 v161, v187
	v_mov_b32_e32 v162, v188
	v_mov_b32_e32 v163, v189
	v_mov_b32_e32 v168, v161
	v_mov_b32_e32 v169, v162
	v_mov_b32_e32 v161, v163
	v_pk_add_f32 v[160:161], v[168:169], v[160:161]
	v_mov_b32_e32 v163, v130
	v_mov_b32_e32 v162, v160
	v_mov_b32_e32 v130, v161
	v_pk_add_f32 v[130:131], v[162:163], v[130:131]
	ds_bpermute_b32 v161, v174, v131
	ds_bpermute_b32 v160, v174, v130
	v_add_u32_e32 v162, 0x90, v142
	v_ashrrev_i32_e32 v163, 31, v162
	s_waitcnt lgkmcnt(0)
	v_pk_add_f32 v[130:131], v[130:131], v[160:161]
	ds_bpermute_b32 v161, v167, v131
	ds_bpermute_b32 v160, v167, v130
	s_waitcnt lgkmcnt(0)
	v_pk_add_f32 v[130:131], v[130:131], v[160:161]
	s_nop 0
	v_pk_fma_f32 v[130:131], v[130:131], s[66:67], v[156:157] op_sel_hi:[1,0,0]
	v_add_u32_e32 v160, 0x80, v142
	v_mul_f32_e32 v154, 0x4b800000, v131
	v_cmp_gt_f32_e64 s[4:5], s80, v131
	v_cmp_gt_f32_e32 vcc, s80, v130
	v_ashrrev_i32_e32 v161, 31, v160
	v_cndmask_b32_e64 v131, v131, v154, s[4:5]
	v_rsq_f32_e32 v131, v131
	s_nop 0
	v_mul_f32_e32 v154, 0x45800000, v131
	v_cndmask_b32_e64 v158, v131, v154, s[4:5]
	v_mul_f32_e32 v131, 0x4b800000, v130
	v_cndmask_b32_e32 v130, v130, v131, vcc
	v_rsq_f32_e32 v130, v130
	v_pk_mul_f32 v[92:93], v[92:93], v[158:159] op_sel_hi:[1,0]
	v_pk_mul_f32 v[94:95], v[94:95], v[158:159] op_sel_hi:[1,0]
	v_pk_mul_f32 v[86:87], v[86:87], v[158:159] op_sel_hi:[1,0]
	v_mul_f32_e32 v131, 0x45800000, v130
	v_cndmask_b32_e32 v154, v130, v131, vcc
	v_lshlrev_b64 v[130:131], 6, v[160:161]
	v_lshl_add_u64 v[130:131], v[128:129], 0, v[130:131]
	v_mov_b32_e32 v168, v198
	v_mov_b32_e32 v169, v199
	v_mov_b32_e32 v170, v200
	v_mov_b32_e32 v171, v201
	v_pk_mul_f32 v[84:85], v[84:85], v[158:159] op_sel_hi:[1,0]
	v_pk_mul_f32 v[76:77], v[76:77], v[154:155] op_sel_hi:[1,0]
	v_pk_mul_f32 v[78:79], v[78:79], v[154:155] op_sel_hi:[1,0]
	v_pk_mul_f32 v[70:71], v[70:71], v[154:155] op_sel_hi:[1,0]
	v_pk_mul_f32 v[68:69], v[68:69], v[154:155] op_sel_hi:[1,0]
	v_mov_b32_e32 v130, v169
	v_mov_b32_e32 v131, v170
	v_mov_b32_e32 v169, v171
	v_pk_add_f32 v[130:131], v[130:131], v[168:169]
	v_lshlrev_b64 v[168:169], 6, v[162:163]
	v_lshl_add_u64 v[168:169], v[128:129], 0, v[168:169]
	v_mov_b32_e32 v168, v218
	v_mov_b32_e32 v169, v219
	v_mov_b32_e32 v170, v220
	v_mov_b32_e32 v171, v221
	v_mov_b32_e32 v172, v169
	v_mov_b32_e32 v173, v170
	v_mov_b32_e32 v169, v171
	v_pk_add_f32 v[168:169], v[172:173], v[168:169]
	v_mov_b32_e32 v171, v130
	v_mov_b32_e32 v170, v168
	v_mov_b32_e32 v130, v169
	v_pk_add_f32 v[130:131], v[170:171], v[130:131]
	ds_bpermute_b32 v169, v174, v131
	ds_bpermute_b32 v168, v174, v130
	s_waitcnt lgkmcnt(0)
	v_pk_add_f32 v[130:131], v[130:131], v[168:169]
	ds_bpermute_b32 v169, v167, v131
	ds_bpermute_b32 v168, v167, v130
	s_waitcnt lgkmcnt(0)
	v_pk_add_f32 v[130:131], v[130:131], v[168:169]
	s_nop 0
	v_pk_fma_f32 v[130:131], v[130:131], s[66:67], v[156:157] op_sel_hi:[1,0,0]
	v_add_u32_e32 v168, 0xa0, v142
	v_mul_f32_e32 v164, 0x4b800000, v131
	v_cmp_gt_f32_e64 s[4:5], s80, v131
	v_cmp_gt_f32_e32 vcc, s80, v130
	v_ashrrev_i32_e32 v169, 31, v168
	v_cndmask_b32_e64 v131, v131, v164, s[4:5]
	v_rsq_f32_e32 v131, v131
	s_nop 0
	v_mul_f32_e32 v164, 0x45800000, v131
	v_cndmask_b32_e64 v166, v131, v164, s[4:5]
	v_mul_f32_e32 v131, 0x4b800000, v130
	v_cndmask_b32_e32 v130, v130, v131, vcc
	v_rsq_f32_e32 v130, v130
	v_pk_mul_f32 v[60:61], v[60:61], v[166:167] op_sel_hi:[1,0]
	v_pk_mul_f32 v[62:63], v[62:63], v[166:167] op_sel_hi:[1,0]
	v_pk_mul_f32 v[54:55], v[54:55], v[166:167] op_sel_hi:[1,0]
	v_mul_f32_e32 v131, 0x45800000, v130
	v_cndmask_b32_e32 v164, v130, v131, vcc
	v_lshlrev_b64 v[130:131], 6, v[168:169]
	v_lshl_add_u64 v[130:131], v[128:129], 0, v[130:131]
	v_mov_b32_e32 v170, v222
	v_mov_b32_e32 v171, v223
	v_mov_b32_e32 v172, v224
	v_mov_b32_e32 v173, v225
	v_pk_mul_f32 v[52:53], v[52:53], v[166:167] op_sel_hi:[1,0]
	v_pk_mul_f32 v[44:45], v[44:45], v[164:165] op_sel_hi:[1,0]
	v_pk_mul_f32 v[46:47], v[46:47], v[164:165] op_sel_hi:[1,0]
	v_pk_mul_f32 v[38:39], v[38:39], v[164:165] op_sel_hi:[1,0]
	v_pk_mul_f32 v[36:37], v[36:37], v[164:165] op_sel_hi:[1,0]
	v_mov_b32_e32 v130, v171
	v_mov_b32_e32 v131, v172
	v_mov_b32_e32 v171, v173
	v_pk_add_f32 v[172:173], v[130:131], v[170:171]
	v_add_u32_e32 v170, 0xb0, v142
	v_ashrrev_i32_e32 v171, 31, v170
	v_lshlrev_b64 v[130:131], 6, v[170:171]
	v_lshl_add_u64 v[128:129], v[128:129], 0, v[130:131]
	v_mov_b32_e32 v128, v226
	v_mov_b32_e32 v129, v227
	v_mov_b32_e32 v130, v228
	v_mov_b32_e32 v131, v229
	v_mov_b32_e32 v176, v129
	v_mov_b32_e32 v177, v130
	v_mov_b32_e32 v129, v131
	v_pk_add_f32 v[128:129], v[176:177], v[128:129]
	v_mov_b32_e32 v131, v172
	v_mov_b32_e32 v130, v128
	v_mov_b32_e32 v172, v129
	v_pk_add_f32 v[128:129], v[130:131], v[172:173]
	ds_bpermute_b32 v131, v174, v129
	ds_bpermute_b32 v130, v174, v128
	v_pk_mul_f32 v[172:173], v[122:123], v[148:149] op_sel_hi:[1,0]
	v_cvt_pk_bf16_f32 v122, v124, v125
	v_cvt_pk_bf16_f32 v124, v120, v121
	v_lshlrev_b64 v[120:121], 9, v[142:143]
	s_waitcnt lgkmcnt(0)
	v_pk_add_f32 v[128:129], v[128:129], v[130:131]
	ds_bpermute_b32 v131, v167, v129
	ds_bpermute_b32 v130, v167, v128
	v_cvt_pk_bf16_f32 v123, v126, v127
	v_cvt_pk_bf16_f32 v125, v172, v173
	s_waitcnt lgkmcnt(0)
	v_pk_add_f32 v[128:129], v[128:129], v[130:131]
	s_nop 0
	v_pk_fma_f32 v[128:129], v[128:129], s[66:67], v[156:157] op_sel_hi:[1,0,0]
	s_nop 0
	v_mul_f32_e32 v130, 0x4b800000, v129
	v_cmp_gt_f32_e64 s[4:5], s80, v129
	v_cmp_gt_f32_e32 vcc, s80, v128
	s_nop 0
	v_cndmask_b32_e64 v129, v129, v130, s[4:5]
	v_rsq_f32_e32 v129, v129
	s_nop 0
	v_mul_f32_e32 v130, 0x45800000, v129
	v_cndmask_b32_e64 v130, v129, v130, s[4:5]
	s_lshl_b32 s4, s54, 8
	s_or_b32 s4, s4, s35
	v_lshl_add_u32 v156, v165, 3, s4
	v_readlane_b32 s4, v253, 62
	v_ashrrev_i32_e32 v157, 31, v156
	v_readlane_b32 s5, v253, 63
	v_mul_f32_e32 v129, 0x4b800000, v128
	v_cndmask_b32_e32 v128, v128, v129, vcc
	v_lshl_add_u64 v[126:127], s[4:5], 0, v[120:121]
	v_lshlrev_b64 v[120:121], 1, v[156:157]
	v_lshl_add_u64 v[126:127], v[126:127], 0, v[120:121]
	global_store_dwordx4 v[126:127], v[122:125], off
	v_rsq_f32_e32 v128, v128
	v_pk_mul_f32 v[28:29], v[28:29], v[130:131] op_sel_hi:[1,0]
	v_pk_mul_f32 v[122:123], v[114:115], v[148:149] op_sel_hi:[1,0]
	v_pk_mul_f32 v[114:115], v[112:113], v[148:149] op_sel_hi:[1,0]
	v_cvt_pk_bf16_f32 v112, v116, v117
	v_cvt_pk_bf16_f32 v113, v118, v119
	v_cvt_pk_bf16_f32 v114, v114, v115
	v_cvt_pk_bf16_f32 v115, v122, v123
	global_store_dwordx4 v[126:127], v[112:115], off offset:256
	v_pk_mul_f32 v[30:31], v[30:31], v[130:131] op_sel_hi:[1,0]
	v_mul_f32_e32 v129, 0x45800000, v128
	v_pk_mul_f32 v[112:113], v[106:107], v[146:147] op_sel_hi:[1,0]
	v_pk_mul_f32 v[106:107], v[104:105], v[146:147] op_sel_hi:[1,0]
	v_cvt_pk_bf16_f32 v104, v108, v109
	v_lshlrev_b64 v[108:109], 9, v[144:145]
	v_lshl_add_u64 v[108:109], s[4:5], 0, v[108:109]
	v_cvt_pk_bf16_f32 v105, v110, v111
	v_cvt_pk_bf16_f32 v106, v106, v107
	v_cvt_pk_bf16_f32 v107, v112, v113
	v_lshl_add_u64 v[108:109], v[108:109], 0, v[120:121]
	global_store_dwordx4 v[108:109], v[104:107], off
	v_cndmask_b32_e32 v128, v128, v129, vcc
	v_pk_mul_f32 v[22:23], v[22:23], v[130:131] op_sel_hi:[1,0]
	v_pk_mul_f32 v[104:105], v[98:99], v[146:147] op_sel_hi:[1,0]
	v_pk_mul_f32 v[98:99], v[96:97], v[146:147] op_sel_hi:[1,0]
	v_cvt_pk_bf16_f32 v96, v100, v101
	v_cvt_pk_bf16_f32 v97, v102, v103
	v_cvt_pk_bf16_f32 v98, v98, v99
	v_cvt_pk_bf16_f32 v99, v104, v105
	global_store_dwordx4 v[108:109], v[96:99], off offset:256
	v_pk_mul_f32 v[20:21], v[20:21], v[130:131] op_sel_hi:[1,0]
	v_pk_mul_f32 v[12:13], v[12:13], v[128:129] op_sel_hi:[1,0]
	v_pk_mul_f32 v[96:97], v[90:91], v[158:159] op_sel_hi:[1,0]
	v_pk_mul_f32 v[90:91], v[88:89], v[158:159] op_sel_hi:[1,0]
	v_cvt_pk_bf16_f32 v88, v92, v93
	v_lshlrev_b64 v[92:93], 9, v[152:153]
	v_lshl_add_u64 v[92:93], s[4:5], 0, v[92:93]
	v_cvt_pk_bf16_f32 v89, v94, v95
	v_cvt_pk_bf16_f32 v90, v90, v91
	v_cvt_pk_bf16_f32 v91, v96, v97
	v_lshl_add_u64 v[92:93], v[92:93], 0, v[120:121]
	global_store_dwordx4 v[92:93], v[88:91], off
	v_pk_mul_f32 v[14:15], v[14:15], v[128:129] op_sel_hi:[1,0]
	v_pk_mul_f32 v[6:7], v[6:7], v[128:129] op_sel_hi:[1,0]
	v_pk_mul_f32 v[88:89], v[82:83], v[158:159] op_sel_hi:[1,0]
	v_pk_mul_f32 v[82:83], v[80:81], v[158:159] op_sel_hi:[1,0]
	v_cvt_pk_bf16_f32 v80, v84, v85
	v_cvt_pk_bf16_f32 v81, v86, v87
	v_cvt_pk_bf16_f32 v82, v82, v83
	v_cvt_pk_bf16_f32 v83, v88, v89
	global_store_dwordx4 v[92:93], v[80:83], off offset:256
	v_pk_mul_f32 v[4:5], v[4:5], v[128:129] op_sel_hi:[1,0]
	s_and_b64 vcc, exec, s[0:1]
	v_pk_mul_f32 v[80:81], v[74:75], v[154:155] op_sel_hi:[1,0]
	v_pk_mul_f32 v[74:75], v[72:73], v[154:155] op_sel_hi:[1,0]
	v_cvt_pk_bf16_f32 v72, v76, v77
	v_lshlrev_b64 v[76:77], 9, v[150:151]
	v_lshl_add_u64 v[76:77], s[4:5], 0, v[76:77]
	v_cvt_pk_bf16_f32 v73, v78, v79
	v_cvt_pk_bf16_f32 v74, v74, v75
	v_cvt_pk_bf16_f32 v75, v80, v81
	v_lshl_add_u64 v[76:77], v[76:77], 0, v[120:121]
	global_store_dwordx4 v[76:77], v[72:75], off
	s_nop 1
	v_pk_mul_f32 v[72:73], v[66:67], v[154:155] op_sel_hi:[1,0]
	v_pk_mul_f32 v[66:67], v[64:65], v[154:155] op_sel_hi:[1,0]
	v_cvt_pk_bf16_f32 v64, v68, v69
	v_cvt_pk_bf16_f32 v65, v70, v71
	v_cvt_pk_bf16_f32 v66, v66, v67
	v_cvt_pk_bf16_f32 v67, v72, v73
	global_store_dwordx4 v[76:77], v[64:67], off offset:256
	s_nop 1
	v_pk_mul_f32 v[64:65], v[58:59], v[166:167] op_sel_hi:[1,0]
	v_pk_mul_f32 v[58:59], v[56:57], v[166:167] op_sel_hi:[1,0]
	v_cvt_pk_bf16_f32 v56, v60, v61
	v_lshlrev_b64 v[60:61], 9, v[160:161]
	v_lshl_add_u64 v[60:61], s[4:5], 0, v[60:61]
	v_cvt_pk_bf16_f32 v57, v62, v63
	v_cvt_pk_bf16_f32 v58, v58, v59
	v_cvt_pk_bf16_f32 v59, v64, v65
	v_lshl_add_u64 v[60:61], v[60:61], 0, v[120:121]
	global_store_dwordx4 v[60:61], v[56:59], off
	s_nop 1
	v_pk_mul_f32 v[56:57], v[50:51], v[166:167] op_sel_hi:[1,0]
	v_pk_mul_f32 v[50:51], v[48:49], v[166:167] op_sel_hi:[1,0]
	v_cvt_pk_bf16_f32 v48, v52, v53
	v_cvt_pk_bf16_f32 v49, v54, v55
	v_cvt_pk_bf16_f32 v50, v50, v51
	v_cvt_pk_bf16_f32 v51, v56, v57
	global_store_dwordx4 v[60:61], v[48:51], off offset:256
	s_nop 1
	v_pk_mul_f32 v[48:49], v[42:43], v[164:165] op_sel_hi:[1,0]
	v_pk_mul_f32 v[42:43], v[40:41], v[164:165] op_sel_hi:[1,0]
	v_cvt_pk_bf16_f32 v40, v44, v45
	v_lshlrev_b64 v[44:45], 9, v[162:163]
	v_lshl_add_u64 v[44:45], s[4:5], 0, v[44:45]
	v_cvt_pk_bf16_f32 v41, v46, v47
	v_cvt_pk_bf16_f32 v42, v42, v43
	v_cvt_pk_bf16_f32 v43, v48, v49
	v_lshl_add_u64 v[44:45], v[44:45], 0, v[120:121]
	global_store_dwordx4 v[44:45], v[40:43], off
	s_nop 1
	v_pk_mul_f32 v[40:41], v[34:35], v[164:165] op_sel_hi:[1,0]
	v_pk_mul_f32 v[34:35], v[32:33], v[164:165] op_sel_hi:[1,0]
	v_cvt_pk_bf16_f32 v32, v36, v37
	v_cvt_pk_bf16_f32 v33, v38, v39
	v_cvt_pk_bf16_f32 v34, v34, v35
	v_cvt_pk_bf16_f32 v35, v40, v41
	global_store_dwordx4 v[44:45], v[32:35], off offset:256
	s_nop 1
	v_pk_mul_f32 v[32:33], v[26:27], v[130:131] op_sel_hi:[1,0]
	v_pk_mul_f32 v[26:27], v[24:25], v[130:131] op_sel_hi:[1,0]
	v_cvt_pk_bf16_f32 v24, v28, v29
	v_lshlrev_b64 v[28:29], 9, v[168:169]
	v_lshl_add_u64 v[28:29], s[4:5], 0, v[28:29]
	v_cvt_pk_bf16_f32 v25, v30, v31
	v_cvt_pk_bf16_f32 v26, v26, v27
	v_cvt_pk_bf16_f32 v27, v32, v33
	v_lshl_add_u64 v[28:29], v[28:29], 0, v[120:121]
	global_store_dwordx4 v[28:29], v[24:27], off
	s_nop 1
	v_pk_mul_f32 v[24:25], v[18:19], v[130:131] op_sel_hi:[1,0]
	v_pk_mul_f32 v[18:19], v[16:17], v[130:131] op_sel_hi:[1,0]
	v_cvt_pk_bf16_f32 v16, v20, v21
	v_cvt_pk_bf16_f32 v17, v22, v23
	v_cvt_pk_bf16_f32 v18, v18, v19
	v_cvt_pk_bf16_f32 v19, v24, v25
	global_store_dwordx4 v[28:29], v[16:19], off offset:256
	s_nop 1
	v_pk_mul_f32 v[16:17], v[10:11], v[128:129] op_sel_hi:[1,0]
	v_pk_mul_f32 v[10:11], v[8:9], v[128:129] op_sel_hi:[1,0]
	v_cvt_pk_bf16_f32 v8, v12, v13
	v_lshlrev_b64 v[12:13], 9, v[170:171]
	v_lshl_add_u64 v[12:13], s[4:5], 0, v[12:13]
	v_cvt_pk_bf16_f32 v9, v14, v15
	v_cvt_pk_bf16_f32 v10, v10, v11
	v_cvt_pk_bf16_f32 v11, v16, v17
	v_lshl_add_u64 v[12:13], v[12:13], 0, v[120:121]
	global_store_dwordx4 v[12:13], v[8:11], off
	s_mov_b64 s[4:5], -1
	s_nop 0
	v_pk_mul_f32 v[8:9], v[2:3], v[128:129] op_sel_hi:[1,0]
	v_pk_mul_f32 v[2:3], v[0:1], v[128:129] op_sel_hi:[1,0]
	v_cvt_pk_bf16_f32 v0, v4, v5
	v_cvt_pk_bf16_f32 v1, v6, v7
	v_cvt_pk_bf16_f32 v2, v2, v3
	v_cvt_pk_bf16_f32 v3, v8, v9
	global_store_dwordx4 v[12:13], v[0:3], off offset:256
	s_cbranch_vccnz .LBB0_769
	s_andn2_b64 vcc, exec, s[14:15]
	s_cbranch_vccnz .LBB0_768
	s_barrier
	s_branch .LBB0_768
